# relax first two vmcnt waits after each SwiGLU unit epilogue (P1,P9): 8 epilogue stores may stay outstanding; drop redundant vmcnt(0) before P9 loop
# speedup vs baseline: 1.0032x; 1.0001x over previous
; #define PG8_STAGE(bufoff, gbase, voff) do { _Pragma("unroll") for (int _i = 0; _i < 2; ++_i) \
;         __builtin_amdgcn_global_load_lds((const unsigned*)((const char*)(gbase) + (voff)[_i]), (LAS unsigned*)(lds + (bufoff) + ldsw + _i * 8192), 16, 0, 0); } while (0)
; #define PG8_WAIT_V(n) asm volatile("s_waitcnt vmcnt(" #n ")" ::: "memory")
; #define PG8_BAR __builtin_amdgcn_s_barrier()
; template <class Epi>
; __device__ __forceinline__ void gemm_phase(LAS unsigned char* lds, const Gemm g, const Sched& S, const Epi& E) {
;     ...
;     for (int i = 0; i < 2; ++i) { int R, C; stage_rc(tid * 16 + i * 8192, R, C); const int Rb = (R & ~31) + perm32(R & 31);
;         voffA[i] = (unsigned)(R * g.lda + C) * 2u; voffB[i] = (unsigned)(Rb * g.ldb + C) * 2u; }
;     const size_t kstep = (size_t)(BK * 2);
;     const size_t hstepA = (size_t)HALF * g.lda * 2, hstepB = (size_t)HALF * g.ldb * 2;
;     const size_t tstepA = 2 * hstepA, tstepB = 2 * hstepB;
;     const unsigned ldsw = (unsigned)wid * 1024u;
;     const int aoff = lds_byte(wr * 64 + fr, fq * 8), boff = lds_byte(wc * 32 + fr, fq * 8);
;     ...
;     PG8_STAGE(PG8_SB(0, 0), cB, voffB); PG8_STAGE(PG8_SB(0, 1), cB + hstepB, voffB); PG8_STAGE(PG8_SA(0, 0), cA, voffA); PG8_STAGE(PG8_SA(0, 1), cA + hstepA, voffA);
;     if (wr == 1) PG8_BAR;
;     PG8_WAIT_V(2); PG8_BAR;
;     PG8_STAGE(PG8_SB(1, 0), cB + kstep, voffB); PG8_STAGE(PG8_SA(1, 0), cA + kstep, voffA); PG8_STAGE(PG8_SB(1, 1), cB + hstepB + kstep, voffB);
;     PG8_WAIT_V(6); PG8_BAR;
;     for (;;) {
;         const bool has_next = S.next(ui + 1, nxt);
.LBB0_574:
	s_lshl_b32 s6, s6, 5
	s_and_b32 s20, s6, 0x60
	s_mov_b64 s[6:7], 0x80
	s_add_i32 m0, s25, 0x18000
	v_lshl_add_u64 v[8:9], v[8:9], 0, s[6:7]
	s_lshl_b32 s9, s1, 13
	s_lshl_b32 s21, s20, 7
	s_waitcnt vmcnt(2)
	s_barrier
	global_load_lds_dwordx4 v[8:9], off
	v_lshl_add_u64 v[6:7], v[6:7], 0, s[6:7]
	s_add_i32 m0, s25, 0x1a000
	s_add_i32 s54, s25, 0x8000
	s_add_i32 s55, s25, 0xa000
	global_load_lds_dwordx4 v[6:7], off
	v_lshl_add_u64 v[2:3], v[2:3], 0, s[6:7]
	s_mov_b32 m0, s54
	s_add_u32 s18, s38, 0x40080
	global_load_lds_dwordx4 v[2:3], off
	v_lshl_add_u64 v[2:3], v[4:5], 0, s[6:7]
	s_mov_b32 m0, s55
	s_addc_u32 s19, s39, 0
	global_load_lds_dwordx4 v[2:3], off
	s_add_i32 m0, s25, 0x1c000
	v_lshl_add_u64 v[2:3], s[18:19], 0, v[132:133]
	global_load_lds_dwordx4 v[2:3], off
	v_lshl_add_u64 v[2:3], s[18:19], 0, v[136:137]
	s_add_i32 m0, s25, 0x1e000
	s_sext_i32_i8 s79, s0
	global_load_lds_dwordx4 v[2:3], off
	v_and_b32_e32 v2, 15, v0
	v_lshlrev_b32_e32 v3, 1, v13
	v_lshl_or_b32 v146, s1, 6, v2
	v_lshl_or_b32 v4, v2, 6, v3
	v_lshlrev_b32_e32 v2, 2, v2
	v_and_b32_e32 v5, 32, v2
	v_bitop3_b32 v4, v4, s9, v5 bitop3:0xde
	v_lshlrev_b32_e32 v5, 6, v0
	s_movk_i32 s0, 0x3c0
	v_and_or_b32 v3, v5, s0, v3
	s_lshl_b32 s0, s1, 8
	s_add_i32 s0, s0, 0
	v_lshlrev_b32_e32 v5, 2, v0
	s_add_i32 s0, s0, 0x20800
	v_and_b32_e32 v5, 32, v5
	v_add_u32_e32 v148, s0, v2
	v_lshlrev_b32_e32 v2, 8, v0
	v_bitop3_b32 v147, s21, v3, v5 bitop3:0xf6
	v_and_b32_e32 v2, 0x18000, v2
	v_lshlrev_b32_e32 v3, 11, v12
	v_or3_b32 v2, v10, v2, v3
	v_add_u32_e32 v138, v2, v11
	v_lshlrev_b32_e32 v2, 4, v14
	s_waitcnt vmcnt(6)
	s_cmpk_lt_u32 s8, 0x100
	v_and_b32_e32 v2, 0x38000, v2
	s_cselect_b64 s[8:9], -1, 0
	v_or3_b32 v2, v10, v2, v3
	s_add_i32 s72, 0, 0x10000
	s_add_i32 s73, 0, 0x14000
	v_or_b32_e32 v149, 16, v146
	v_or_b32_e32 v150, 32, v146
	v_or_b32_e32 v151, 48, v146
	v_or_b32_e32 v152, s20, v13
	v_mov_b32_e32 v139, v133
	v_add_u32_e32 v140, v2, v11
	v_mov_b32_e32 v141, v133
	v_mov_b64_e32 v[142:143], 0x596
	v_mov_b64_e32 v[144:145], 0x595
	v_add_u32_e32 v153, s72, v147
	v_add_u32_e32 v154, s73, v147
	v_add_u32_e32 v155, 0, v4
	s_movk_i32 s74, 0x1600
	s_mov_b32 s75, 0
	s_barrier
	s_mov_b32 s98, 0
	s_branch .LBB0_577
.LBB0_575:
	s_mov_b64 s[0:1], 0
	s_mov_b32 s98, 2

; #define PG8_STAGE(bufoff, gbase, voff) do { _Pragma("unroll") for (int _i = 0; _i < 2; ++_i) \
;         __builtin_amdgcn_global_load_lds((const unsigned*)((const char*)(gbase) + (voff)[_i]), (LAS unsigned*)(lds + (bufoff) + ldsw + _i * 8192), 16, 0, 0); } while (0)
; #define PG8_LDA(dst, b, h) do { _Pragma("unroll") for (int m = 0; m < 4; ++m) _Pragma("unroll") for (int k = 0; k < 2; ++k) dst[m][k] = *(const LAS bf16x8*)(lds + PG8_SA(b, h) + aoff + m * 2048 + k * 1024); } while (0)
; #define PG8_LDB(dst, b, h) do { _Pragma("unroll") for (int n = 0; n < 2; ++n) _Pragma("unroll") for (int k = 0; k < 2; ++k) dst[n][k] = *(const LAS bf16x8*)(lds + PG8_SB(b, h) + boff + n * 2048 + k * 1024); } while (0)
; #define PG8_MMA(ai, bj, At, Bt) do { __builtin_amdgcn_s_setprio(1); _Pragma("unroll") for (int m = 0; m < 4; ++m) _Pragma("unroll") for (int n = 0; n < 2; ++n) _Pragma("unroll") for (int k = 0; k < 2; ++k) \
;         acc[ai][bj][m][n] = __builtin_amdgcn_mfma_f32_16x16x32_bf16(Bt[n][k], At[m][k], acc[ai][bj][m][n], 0, 0, 0); __builtin_amdgcn_s_setprio(0); } while (0)
; #define PG8_WAIT_V(n) asm volatile("s_waitcnt vmcnt(" #n ")" ::: "memory")
; #define PG8_WAIT_L(n) asm volatile("s_waitcnt lgkmcnt(" #n ")" ::: "memory")
; #define PG8_BAR __builtin_amdgcn_s_barrier()
; #define PG8_SCHED __builtin_amdgcn_sched_barrier(0)
; template <class Epi>
; __device__ __forceinline__ void gemm_phase(LAS unsigned char* lds, const Gemm g, const Sched& S, const Epi& E) {
;     ...
;             PG8_LDB(B0, 0, 0); PG8_LDB(B1, 0, 1); PG8_SCHED; PG8_LDA(At, 0, 0); PG8_STAGE(PG8_SA(1, 1), a1 + hstepA, voffA);
;             PG8_WAIT_V(8); PG8_WAIT_L(0); PG8_BAR; PG8_MMA(0, 0, At, B0); PG8_MMA(0, 1, At, B1); PG8_BAR; PG8_SCHED;
.LBB0_584:
	ds_read_b128 v[156:159], v153
	ds_read_b128 v[160:163], v153 offset:1024
	ds_read_b128 v[164:167], v153 offset:2048
	ds_read_b128 v[168:171], v153 offset:3072
	ds_read_b128 v[172:175], v154
	ds_read_b128 v[176:179], v154 offset:1024
	ds_read_b128 v[180:183], v154 offset:2048
	ds_read_b128 v[184:187], v154 offset:3072
	s_add_u32 s38, s34, 0xfffc0080
	s_addc_u32 s39, s35, -1
	s_cmp_eq_u32 s86, 12
	s_cselect_b32 s41, s21, s39
	s_cselect_b32 s40, s82, s38
	s_cselect_b32 s39, s19, s85
	s_cselect_b32 s38, s83, s84
	v_lshl_add_u64 v[196:197], s[34:35], 0, v[138:139]
	s_add_i32 m0, s25, 0xc000
	ds_read_b128 v[188:191], v155
	ds_read_b128 v[192:195], v155 offset:1024
	ds_read_b128 v[200:203], v155 offset:2048
	ds_read_b128 v[204:207], v155 offset:3072
	ds_read_b128 v[208:211], v155 offset:4096
	ds_read_b128 v[212:215], v155 offset:5120
	ds_read_b128 v[216:219], v155 offset:6144
	ds_read_b128 v[220:223], v155 offset:7168
	global_load_lds_dwordx4 v[196:197], off
	v_lshl_add_u64 v[196:197], s[34:35], 0, v[140:141]
	s_add_i32 m0, s25, 0xe000
	s_nop 0
	global_load_lds_dwordx4 v[196:197], off
	s_cmp_eq_u32 s98, 0
	s_cbranch_scc1 .Lrx_p1_0_n
	s_sub_u32 s98, s98, 1
	s_waitcnt vmcnt(16)
	s_branch .Lrx_p1_0_j

; #define PG8_STAGE(bufoff, gbase, voff) do { _Pragma("unroll") for (int _i = 0; _i < 2; ++_i) \
;         __builtin_amdgcn_global_load_lds((const unsigned*)((const char*)(gbase) + (voff)[_i]), (LAS unsigned*)(lds + (bufoff) + ldsw + _i * 8192), 16, 0, 0); } while (0)
; #define PG8_LDA(dst, b, h) do { _Pragma("unroll") for (int m = 0; m < 4; ++m) _Pragma("unroll") for (int k = 0; k < 2; ++k) dst[m][k] = *(const LAS bf16x8*)(lds + PG8_SA(b, h) + aoff + m * 2048 + k * 1024); } while (0)
; #define PG8_MMA(ai, bj, At, Bt) do { __builtin_amdgcn_s_setprio(1); _Pragma("unroll") for (int m = 0; m < 4; ++m) _Pragma("unroll") for (int n = 0; n < 2; ++n) _Pragma("unroll") for (int k = 0; k < 2; ++k) \
;         acc[ai][bj][m][n] = __builtin_amdgcn_mfma_f32_16x16x32_bf16(Bt[n][k], At[m][k], acc[ai][bj][m][n], 0, 0, 0); __builtin_amdgcn_s_setprio(0); } while (0)
; #define PG8_WAIT_V(n) asm volatile("s_waitcnt vmcnt(" #n ")" ::: "memory")
; #define PG8_WAIT_L(n) asm volatile("s_waitcnt lgkmcnt(" #n ")" ::: "memory")
; #define PG8_BAR __builtin_amdgcn_s_barrier()
; #define PG8_SCHED __builtin_amdgcn_sched_barrier(0)
; template <class Epi>
; __device__ __forceinline__ void gemm_phase(LAS unsigned char* lds, const Gemm g, const Sched& S, const Epi& E) {
;     ...
;             PG8_WAIT_V(8); PG8_WAIT_L(0); PG8_BAR; PG8_MMA(0, 0, At, B0); PG8_MMA(0, 1, At, B1); PG8_BAR; PG8_SCHED;
;             PG8_LDA(At, 0, 1); PG8_STAGE(PG8_SB(0, 0), b2, voffB); PG8_STAGE(PG8_SB(0, 1), b2 + hstepB, voffB); PG8_STAGE(PG8_SA(0, 0), a2, voffA);
.Lrx_p1_0_j:
	s_waitcnt lgkmcnt(0)
	s_barrier
	s_setprio 1
	s_waitcnt lgkmcnt(0)
	v_mfma_f32_16x16x32_bf16 v[126:129], v[156:159], v[188:191], v[126:129]
	v_mfma_f32_16x16x32_bf16 v[122:125], v[164:167], v[188:191], v[122:125]
	v_mfma_f32_16x16x32_bf16 v[110:113], v[156:159], v[200:203], v[110:113]
	v_mfma_f32_16x16x32_bf16 v[106:109], v[164:167], v[200:203], v[106:109]
	v_mfma_f32_16x16x32_bf16 v[94:97], v[156:159], v[208:211], v[94:97]
	v_mfma_f32_16x16x32_bf16 v[90:93], v[164:167], v[208:211], v[90:93]
	v_mfma_f32_16x16x32_bf16 v[78:81], v[156:159], v[216:219], v[78:81]
	v_mfma_f32_16x16x32_bf16 v[74:77], v[164:167], v[216:219], v[74:77]
	v_mfma_f32_16x16x32_bf16 v[126:129], v[160:163], v[192:195], v[126:129]
	v_mfma_f32_16x16x32_bf16 v[122:125], v[168:171], v[192:195], v[122:125]
	v_mfma_f32_16x16x32_bf16 v[110:113], v[160:163], v[204:207], v[110:113]
	v_mfma_f32_16x16x32_bf16 v[106:109], v[168:171], v[204:207], v[106:109]
	v_mfma_f32_16x16x32_bf16 v[94:97], v[160:163], v[212:215], v[94:97]
	v_mfma_f32_16x16x32_bf16 v[90:93], v[168:171], v[212:215], v[90:93]
	v_mfma_f32_16x16x32_bf16 v[78:81], v[160:163], v[220:223], v[78:81]
	v_mfma_f32_16x16x32_bf16 v[74:77], v[168:171], v[220:223], v[74:77]
	s_setprio 0
	s_setprio 1
	v_mfma_f32_16x16x32_bf16 v[118:121], v[172:175], v[188:191], v[118:121]
	v_mfma_f32_16x16x32_bf16 v[114:117], v[180:183], v[188:191], v[114:117]
	v_mfma_f32_16x16x32_bf16 v[102:105], v[172:175], v[200:203], v[102:105]
	v_mfma_f32_16x16x32_bf16 v[98:101], v[180:183], v[200:203], v[98:101]
	v_mfma_f32_16x16x32_bf16 v[86:89], v[172:175], v[208:211], v[86:89]
	v_mfma_f32_16x16x32_bf16 v[82:85], v[180:183], v[208:211], v[82:85]
	v_mfma_f32_16x16x32_bf16 v[70:73], v[172:175], v[216:219], v[70:73]
	v_mfma_f32_16x16x32_bf16 v[66:69], v[180:183], v[216:219], v[66:69]
	v_mfma_f32_16x16x32_bf16 v[118:121], v[176:179], v[192:195], v[118:121]
	v_mfma_f32_16x16x32_bf16 v[114:117], v[184:187], v[192:195], v[114:117]
	v_mfma_f32_16x16x32_bf16 v[102:105], v[176:179], v[204:207], v[102:105]
	v_mfma_f32_16x16x32_bf16 v[98:101], v[184:187], v[204:207], v[98:101]
	v_mfma_f32_16x16x32_bf16 v[86:89], v[176:179], v[212:215], v[86:89]
	v_mfma_f32_16x16x32_bf16 v[82:85], v[184:187], v[212:215], v[82:85]
	v_mfma_f32_16x16x32_bf16 v[70:73], v[176:179], v[220:223], v[70:73]
	v_mfma_f32_16x16x32_bf16 v[66:69], v[184:187], v[220:223], v[66:69]
	s_setprio 0
	s_barrier
	s_add_i32 s87, s72, s24
	v_lshl_add_u64 v[196:197], s[38:39], 0, v[132:133]
	s_mov_b32 m0, s87
	ds_read_b128 v[188:191], v155 offset:16384
	ds_read_b128 v[192:195], v155 offset:17408
	ds_read_b128 v[200:203], v155 offset:18432
	ds_read_b128 v[204:207], v155 offset:19456
	ds_read_b128 v[208:211], v155 offset:20480
	ds_read_b128 v[212:215], v155 offset:21504
	ds_read_b128 v[216:219], v155 offset:22528
	ds_read_b128 v[220:223], v155 offset:23552
	global_load_lds_dwordx4 v[196:197], off
	s_add_i32 m0, s87, 0x2000
	s_add_u32 s88, s38, 0x40000
	v_lshl_add_u64 v[224:225], s[38:39], 0, v[136:137]
	s_addc_u32 s89, s39, 0
	s_add_i32 s87, s73, s24
	global_load_lds_dwordx4 v[224:225], off
	v_lshl_add_u64 v[226:227], s[88:89], 0, v[132:133]
	s_mov_b32 m0, s87
	v_lshl_add_u64 v[228:229], s[40:41], 0, v[134:135]
	global_load_lds_dwordx4 v[226:227], off
	v_lshl_add_u64 v[226:227], s[88:89], 0, v[136:137]
	s_add_i32 m0, s87, 0x2000
	s_nop 0
	global_load_lds_dwordx4 v[226:227], off
	v_lshl_add_u64 v[226:227], s[40:41], 0, v[130:131]
	s_mov_b32 m0, s25
	s_nop 0
	global_load_lds_dwordx4 v[226:227], off
	s_mov_b32 m0, s31
	s_nop 0
	global_load_lds_dwordx4 v[228:229], off
	s_cmp_eq_u32 s98, 0
	s_cbranch_scc1 .Lrx_p1_1_n
	s_sub_u32 s98, s98, 1
	s_waitcnt vmcnt(16)
	s_branch .Lrx_p1_1_j

; #define PG8_STAGE(bufoff, gbase, voff) do { _Pragma("unroll") for (int _i = 0; _i < 2; ++_i) \
;         __builtin_amdgcn_global_load_lds((const unsigned*)((const char*)(gbase) + (voff)[_i]), (LAS unsigned*)(lds + (bufoff) + ldsw + _i * 8192), 16, 0, 0); } while (0)
; #define PG8_LDA(dst, b, h) do { _Pragma("unroll") for (int m = 0; m < 4; ++m) _Pragma("unroll") for (int k = 0; k < 2; ++k) dst[m][k] = *(const LAS bf16x8*)(lds + PG8_SA(b, h) + aoff + m * 2048 + k * 1024); } while (0)
; #define PG8_LDB(dst, b, h) do { _Pragma("unroll") for (int n = 0; n < 2; ++n) _Pragma("unroll") for (int k = 0; k < 2; ++k) dst[n][k] = *(const LAS bf16x8*)(lds + PG8_SB(b, h) + boff + n * 2048 + k * 1024); } while (0)
; #define PG8_MMA(ai, bj, At, Bt) do { __builtin_amdgcn_s_setprio(1); _Pragma("unroll") for (int m = 0; m < 4; ++m) _Pragma("unroll") for (int n = 0; n < 2; ++n) _Pragma("unroll") for (int k = 0; k < 2; ++k) \
;         acc[ai][bj][m][n] = __builtin_amdgcn_mfma_f32_16x16x32_bf16(Bt[n][k], At[m][k], acc[ai][bj][m][n], 0, 0, 0); __builtin_amdgcn_s_setprio(0); } while (0)
; #define PG8_WAIT_V(n) asm volatile("s_waitcnt vmcnt(" #n ")" ::: "memory")
; #define PG8_WAIT_L(n) asm volatile("s_waitcnt lgkmcnt(" #n ")" ::: "memory")
; #define PG8_BAR __builtin_amdgcn_s_barrier()
; #define PG8_SCHED __builtin_amdgcn_sched_barrier(0)
; template <class Epi>
; __device__ __forceinline__ void gemm_phase(LAS unsigned char* lds, const Gemm g, const Sched& S, const Epi& E) {
;     ...
;             PG8_WAIT_V(8); PG8_WAIT_L(0); PG8_BAR; PG8_MMA(1, 0, At, B0); PG8_MMA(1, 1, At, B1); PG8_BAR; PG8_SCHED;
;             PG8_LDB(B0, 1, 0); PG8_LDB(B1, 1, 1); PG8_SCHED; PG8_LDA(At, 1, 0); PG8_STAGE(PG8_SA(0, 1), a2 + hstepA, voffA);
;             PG8_WAIT_V(8); PG8_WAIT_L(0); PG8_BAR; PG8_MMA(0, 0, At, B0); PG8_MMA(0, 1, At, B1); PG8_BAR; PG8_SCHED;
.Lrx_p1_1_j:
	s_waitcnt lgkmcnt(0)
	s_barrier
	s_setprio 1
	s_waitcnt lgkmcnt(0)
	v_mfma_f32_16x16x32_bf16 v[62:65], v[156:159], v[188:191], v[62:65]
	v_mfma_f32_16x16x32_bf16 v[58:61], v[164:167], v[188:191], v[58:61]
	v_mfma_f32_16x16x32_bf16 v[46:49], v[156:159], v[200:203], v[46:49]
	v_mfma_f32_16x16x32_bf16 v[42:45], v[164:167], v[200:203], v[42:45]
	v_mfma_f32_16x16x32_bf16 v[30:33], v[156:159], v[208:211], v[30:33]
	v_mfma_f32_16x16x32_bf16 v[26:29], v[164:167], v[208:211], v[26:29]
	v_mfma_f32_16x16x32_bf16 v[14:17], v[156:159], v[216:219], v[14:17]
	v_mfma_f32_16x16x32_bf16 v[10:13], v[164:167], v[216:219], v[10:13]
	v_mfma_f32_16x16x32_bf16 v[62:65], v[160:163], v[192:195], v[62:65]
	v_mfma_f32_16x16x32_bf16 v[58:61], v[168:171], v[192:195], v[58:61]
	v_mfma_f32_16x16x32_bf16 v[46:49], v[160:163], v[204:207], v[46:49]
	v_mfma_f32_16x16x32_bf16 v[42:45], v[168:171], v[204:207], v[42:45]
	v_mfma_f32_16x16x32_bf16 v[30:33], v[160:163], v[212:215], v[30:33]
	v_mfma_f32_16x16x32_bf16 v[26:29], v[168:171], v[212:215], v[26:29]
	v_mfma_f32_16x16x32_bf16 v[14:17], v[160:163], v[220:223], v[14:17]
	v_mfma_f32_16x16x32_bf16 v[10:13], v[168:171], v[220:223], v[10:13]
	s_setprio 0
	s_setprio 1
	v_mfma_f32_16x16x32_bf16 v[54:57], v[172:175], v[188:191], v[54:57]
	v_mfma_f32_16x16x32_bf16 v[50:53], v[180:183], v[188:191], v[50:53]
	v_mfma_f32_16x16x32_bf16 v[38:41], v[172:175], v[200:203], v[38:41]
	v_mfma_f32_16x16x32_bf16 v[34:37], v[180:183], v[200:203], v[34:37]
	v_mfma_f32_16x16x32_bf16 v[22:25], v[172:175], v[208:211], v[22:25]
	v_mfma_f32_16x16x32_bf16 v[18:21], v[180:183], v[208:211], v[18:21]
	v_mfma_f32_16x16x32_bf16 v[6:9], v[172:175], v[216:219], v[6:9]
	v_mfma_f32_16x16x32_bf16 v[2:5], v[180:183], v[216:219], v[2:5]
	v_mfma_f32_16x16x32_bf16 v[54:57], v[176:179], v[192:195], v[54:57]
	v_mfma_f32_16x16x32_bf16 v[50:53], v[184:187], v[192:195], v[50:53]
	v_mfma_f32_16x16x32_bf16 v[38:41], v[176:179], v[204:207], v[38:41]
	v_mfma_f32_16x16x32_bf16 v[34:37], v[184:187], v[204:207], v[34:37]
	v_mfma_f32_16x16x32_bf16 v[22:25], v[176:179], v[212:215], v[22:25]
	v_mfma_f32_16x16x32_bf16 v[18:21], v[184:187], v[212:215], v[18:21]
	v_mfma_f32_16x16x32_bf16 v[6:9], v[176:179], v[220:223], v[6:9]
	v_mfma_f32_16x16x32_bf16 v[2:5], v[184:187], v[220:223], v[2:5]
	s_setprio 0
	s_barrier
	s_add_i32 s87, 0, 0x18000
	s_add_i32 s88, 0, 0x1c000
	v_add_u32_e32 v168, s87, v147
	v_add_u32_e32 v184, s88, v147
	ds_read_b128 v[156:159], v168
	ds_read_b128 v[160:163], v168 offset:1024
	ds_read_b128 v[164:167], v168 offset:2048
	ds_read_b128 v[168:171], v168 offset:3072
	ds_read_b128 v[172:175], v184
	ds_read_b128 v[176:179], v184 offset:1024
	ds_read_b128 v[180:183], v184 offset:2048
	ds_read_b128 v[184:187], v184 offset:3072
	s_add_u32 s40, s40, 0x40000
	s_addc_u32 s41, s41, 0
	s_mov_b32 m0, s52
	v_lshl_add_u64 v[230:231], s[40:41], 0, v[130:131]
	ds_read_b128 v[188:191], v155 offset:32768
	ds_read_b128 v[192:195], v155 offset:33792
	ds_read_b128 v[200:203], v155 offset:34816
	ds_read_b128 v[204:207], v155 offset:35840
	ds_read_b128 v[208:211], v155 offset:36864
	ds_read_b128 v[212:215], v155 offset:37888
	ds_read_b128 v[216:219], v155 offset:38912
	ds_read_b128 v[220:223], v155 offset:39936
	global_load_lds_dwordx4 v[230:231], off
	v_lshl_add_u64 v[230:231], s[40:41], 0, v[134:135]
	s_mov_b32 m0, s53
	s_nop 0
	global_load_lds_dwordx4 v[230:231], off
	s_waitcnt vmcnt(8)
	s_waitcnt lgkmcnt(0)
	s_barrier
	s_setprio 1
	s_waitcnt lgkmcnt(0)
	v_mfma_f32_16x16x32_bf16 v[126:129], v[156:159], v[188:191], v[126:129]
	v_mfma_f32_16x16x32_bf16 v[122:125], v[164:167], v[188:191], v[122:125]
	v_mfma_f32_16x16x32_bf16 v[110:113], v[156:159], v[200:203], v[110:113]
	v_mfma_f32_16x16x32_bf16 v[106:109], v[164:167], v[200:203], v[106:109]
	v_mfma_f32_16x16x32_bf16 v[94:97], v[156:159], v[208:211], v[94:97]
	v_mfma_f32_16x16x32_bf16 v[90:93], v[164:167], v[208:211], v[90:93]
	v_mfma_f32_16x16x32_bf16 v[78:81], v[156:159], v[216:219], v[78:81]
	v_mfma_f32_16x16x32_bf16 v[74:77], v[164:167], v[216:219], v[74:77]
	v_mfma_f32_16x16x32_bf16 v[126:129], v[160:163], v[192:195], v[126:129]
	v_mfma_f32_16x16x32_bf16 v[122:125], v[168:171], v[192:195], v[122:125]
	v_mfma_f32_16x16x32_bf16 v[110:113], v[160:163], v[204:207], v[110:113]
	v_mfma_f32_16x16x32_bf16 v[106:109], v[168:171], v[204:207], v[106:109]
	v_mfma_f32_16x16x32_bf16 v[94:97], v[160:163], v[212:215], v[94:97]
	v_mfma_f32_16x16x32_bf16 v[90:93], v[168:171], v[212:215], v[90:93]
	v_mfma_f32_16x16x32_bf16 v[78:81], v[160:163], v[220:223], v[78:81]
	v_mfma_f32_16x16x32_bf16 v[74:77], v[168:171], v[220:223], v[74:77]
	s_setprio 0
	s_setprio 1
	v_mfma_f32_16x16x32_bf16 v[118:121], v[172:175], v[188:191], v[118:121]
	v_mfma_f32_16x16x32_bf16 v[114:117], v[180:183], v[188:191], v[114:117]
	v_mfma_f32_16x16x32_bf16 v[102:105], v[172:175], v[200:203], v[102:105]
	v_mfma_f32_16x16x32_bf16 v[98:101], v[180:183], v[200:203], v[98:101]
	v_mfma_f32_16x16x32_bf16 v[86:89], v[172:175], v[208:211], v[86:89]
	v_mfma_f32_16x16x32_bf16 v[82:85], v[180:183], v[208:211], v[82:85]
	v_mfma_f32_16x16x32_bf16 v[70:73], v[172:175], v[216:219], v[70:73]
	v_mfma_f32_16x16x32_bf16 v[66:69], v[180:183], v[216:219], v[66:69]
	v_mfma_f32_16x16x32_bf16 v[118:121], v[176:179], v[192:195], v[118:121]
	v_mfma_f32_16x16x32_bf16 v[114:117], v[184:187], v[192:195], v[114:117]
	v_mfma_f32_16x16x32_bf16 v[102:105], v[176:179], v[204:207], v[102:105]
	v_mfma_f32_16x16x32_bf16 v[98:101], v[184:187], v[204:207], v[98:101]
	v_mfma_f32_16x16x32_bf16 v[86:89], v[176:179], v[212:215], v[86:89]
	v_mfma_f32_16x16x32_bf16 v[82:85], v[184:187], v[212:215], v[82:85]
	v_mfma_f32_16x16x32_bf16 v[70:73], v[176:179], v[220:223], v[70:73]
	v_mfma_f32_16x16x32_bf16 v[66:69], v[184:187], v[220:223], v[66:69]
	s_setprio 0
	s_barrier
; #define PG8_STAGE(bufoff, gbase, voff) do { _Pragma("unroll") for (int _i = 0; _i < 2; ++_i) \
;         __builtin_amdgcn_global_load_lds((const unsigned*)((const char*)(gbase) + (voff)[_i]), (LAS unsigned*)(lds + (bufoff) + ldsw + _i * 8192), 16, 0, 0); } while (0)
; #define PG8_LDA(dst, b, h) do { _Pragma("unroll") for (int m = 0; m < 4; ++m) _Pragma("unroll") for (int k = 0; k < 2; ++k) dst[m][k] = *(const LAS bf16x8*)(lds + PG8_SA(b, h) + aoff + m * 2048 + k * 1024); } while (0)
; #define PG8_MMA(ai, bj, At, Bt) do { __builtin_amdgcn_s_setprio(1); _Pragma("unroll") for (int m = 0; m < 4; ++m) _Pragma("unroll") for (int n = 0; n < 2; ++n) _Pragma("unroll") for (int k = 0; k < 2; ++k) \
;         acc[ai][bj][m][n] = __builtin_amdgcn_mfma_f32_16x16x32_bf16(Bt[n][k], At[m][k], acc[ai][bj][m][n], 0, 0, 0); __builtin_amdgcn_s_setprio(0); } while (0)
; #define PG8_WAIT_V(n) asm volatile("s_waitcnt vmcnt(" #n ")" ::: "memory")
; #define PG8_WAIT_L(n) asm volatile("s_waitcnt lgkmcnt(" #n ")" ::: "memory")
; #define PG8_BAR __builtin_amdgcn_s_barrier()
; #define PG8_SCHED __builtin_amdgcn_sched_barrier(0)
; template <class Epi>
; __device__ __forceinline__ void gemm_phase(LAS unsigned char* lds, const Gemm g, const Sched& S, const Epi& E) {
;     ...
;             PG8_WAIT_V(8); PG8_WAIT_L(0); PG8_BAR; PG8_MMA(0, 0, At, B0); PG8_MMA(0, 1, At, B1); PG8_BAR; PG8_SCHED;
;             PG8_LDA(At, 1, 1); PG8_STAGE(PG8_SB(1, 0), b3, voffB); PG8_STAGE(PG8_SB(1, 1), b3 + hstepB, voffB); PG8_STAGE(PG8_SA(1, 0), a3, voffA);
;             PG8_WAIT_V(8); PG8_WAIT_L(0); PG8_BAR; PG8_MMA(1, 0, At, B0); PG8_MMA(1, 1, At, B1); PG8_BAR; PG8_SCHED;
;         }
;         if (wr == 0) PG8_BAR;
	s_add_i32 s40, s87, s24
	v_lshl_add_u64 v[196:197], v[196:197], 0, s[6:7]
	s_mov_b32 m0, s40
	ds_read_b128 v[188:191], v155 offset:49152
	ds_read_b128 v[192:195], v155 offset:50176
	ds_read_b128 v[200:203], v155 offset:51200
	ds_read_b128 v[204:207], v155 offset:52224
	ds_read_b128 v[208:211], v155 offset:53248
	ds_read_b128 v[212:215], v155 offset:54272
	ds_read_b128 v[216:219], v155 offset:55296
	ds_read_b128 v[220:223], v155 offset:56320
	global_load_lds_dwordx4 v[196:197], off
	s_add_i32 m0, s40, 0x2000
	s_add_u32 s38, s38, 0x40080
	v_lshl_add_u64 v[196:197], v[224:225], 0, s[6:7]
	s_addc_u32 s39, s39, 0
	s_add_i32 s40, s88, s24
	global_load_lds_dwordx4 v[196:197], off
	v_lshl_add_u64 v[196:197], s[38:39], 0, v[132:133]
	s_mov_b32 m0, s40
	s_nop 0
	global_load_lds_dwordx4 v[196:197], off
	v_lshl_add_u64 v[196:197], s[38:39], 0, v[136:137]
	s_add_i32 m0, s40, 0x2000
	s_nop 0
	global_load_lds_dwordx4 v[196:197], off
	v_lshl_add_u64 v[196:197], v[226:227], 0, s[6:7]
	s_mov_b32 m0, s54
	s_nop 0
	global_load_lds_dwordx4 v[196:197], off
	v_lshl_add_u64 v[196:197], v[228:229], 0, s[6:7]
	s_mov_b32 m0, s55
	s_nop 0
	global_load_lds_dwordx4 v[196:197], off
	s_waitcnt vmcnt(8)
	s_waitcnt lgkmcnt(0)
	s_barrier
	s_setprio 1
	s_waitcnt lgkmcnt(0)
	v_mfma_f32_16x16x32_bf16 v[62:65], v[156:159], v[188:191], v[62:65]
	v_mfma_f32_16x16x32_bf16 v[58:61], v[164:167], v[188:191], v[58:61]
	v_mfma_f32_16x16x32_bf16 v[46:49], v[156:159], v[200:203], v[46:49]
	v_mfma_f32_16x16x32_bf16 v[42:45], v[164:167], v[200:203], v[42:45]
	v_mfma_f32_16x16x32_bf16 v[30:33], v[156:159], v[208:211], v[30:33]
	v_mfma_f32_16x16x32_bf16 v[26:29], v[164:167], v[208:211], v[26:29]
	v_mfma_f32_16x16x32_bf16 v[14:17], v[156:159], v[216:219], v[14:17]
	v_mfma_f32_16x16x32_bf16 v[10:13], v[164:167], v[216:219], v[10:13]
	v_mfma_f32_16x16x32_bf16 v[62:65], v[160:163], v[192:195], v[62:65]
	v_mfma_f32_16x16x32_bf16 v[58:61], v[168:171], v[192:195], v[58:61]
	v_mfma_f32_16x16x32_bf16 v[46:49], v[160:163], v[204:207], v[46:49]
	v_mfma_f32_16x16x32_bf16 v[42:45], v[168:171], v[204:207], v[42:45]
	v_mfma_f32_16x16x32_bf16 v[30:33], v[160:163], v[212:215], v[30:33]
	v_mfma_f32_16x16x32_bf16 v[26:29], v[168:171], v[212:215], v[26:29]
	v_mfma_f32_16x16x32_bf16 v[14:17], v[160:163], v[220:223], v[14:17]
	v_mfma_f32_16x16x32_bf16 v[10:13], v[168:171], v[220:223], v[10:13]
	s_setprio 0
	s_setprio 1
	v_mfma_f32_16x16x32_bf16 v[54:57], v[172:175], v[188:191], v[54:57]
	v_mfma_f32_16x16x32_bf16 v[50:53], v[180:183], v[188:191], v[50:53]
	v_mfma_f32_16x16x32_bf16 v[38:41], v[172:175], v[200:203], v[38:41]
	v_mfma_f32_16x16x32_bf16 v[34:37], v[180:183], v[200:203], v[34:37]
	v_mfma_f32_16x16x32_bf16 v[22:25], v[172:175], v[208:211], v[22:25]
	v_mfma_f32_16x16x32_bf16 v[18:21], v[180:183], v[208:211], v[18:21]
	v_mfma_f32_16x16x32_bf16 v[6:9], v[172:175], v[216:219], v[6:9]
	v_mfma_f32_16x16x32_bf16 v[2:5], v[180:183], v[216:219], v[2:5]
	v_mfma_f32_16x16x32_bf16 v[54:57], v[176:179], v[192:195], v[54:57]
	v_mfma_f32_16x16x32_bf16 v[50:53], v[184:187], v[192:195], v[50:53]
	v_mfma_f32_16x16x32_bf16 v[38:41], v[176:179], v[204:207], v[38:41]
	v_mfma_f32_16x16x32_bf16 v[34:37], v[184:187], v[204:207], v[34:37]
	v_mfma_f32_16x16x32_bf16 v[22:25], v[176:179], v[212:215], v[22:25]
	v_mfma_f32_16x16x32_bf16 v[18:21], v[184:187], v[212:215], v[18:21]
	v_mfma_f32_16x16x32_bf16 v[6:9], v[176:179], v[220:223], v[6:9]
	v_mfma_f32_16x16x32_bf16 v[2:5], v[184:187], v[220:223], v[2:5]
	s_setprio 0
	s_barrier
	s_add_i32 s86, s86, 2
	s_add_u32 s34, s34, 0x100
	s_addc_u32 s35, s35, 0
	s_add_u32 s84, s84, 0x100
	s_addc_u32 s85, s85, 0
	s_cmp_gt_u32 s86, 13
	s_cbranch_scc0 .LBB0_584
	s_and_b64 vcc, exec, s[8:9]
	s_cbranch_vccz .LBB0_587
	s_barrier

; #define PG8_STAGE(bufoff, gbase, voff) do { _Pragma("unroll") for (int _i = 0; _i < 2; ++_i) \
;         __builtin_amdgcn_global_load_lds((const unsigned*)((const char*)(gbase) + (voff)[_i]), (LAS unsigned*)(lds + (bufoff) + ldsw + _i * 8192), 16, 0, 0); } while (0)
; #define PG8_WAIT_V(n) asm volatile("s_waitcnt vmcnt(" #n ")" ::: "memory")
; #define PG8_BAR __builtin_amdgcn_s_barrier()
; template <class Epi>
; __device__ __forceinline__ void gemm_phase(LAS unsigned char* lds, const Gemm g, const Sched& S, const Epi& E) {
;     ...
;     for (int i = 0; i < 2; ++i) { int R, C; stage_rc(tid * 16 + i * 8192, R, C); const int Rb = (R & ~31) + perm32(R & 31);
;         voffA[i] = (unsigned)(R * g.lda + C) * 2u; voffB[i] = (unsigned)(Rb * g.ldb + C) * 2u; }
;     const size_t kstep = (size_t)(BK * 2);
;     const size_t hstepA = (size_t)HALF * g.lda * 2, hstepB = (size_t)HALF * g.ldb * 2;
;     const size_t tstepA = 2 * hstepA, tstepB = 2 * hstepB;
;     const unsigned ldsw = (unsigned)wid * 1024u;
;     const int aoff = lds_byte(wr * 64 + fr, fq * 8), boff = lds_byte(wc * 32 + fr, fq * 8);
;     ...
;     PG8_STAGE(PG8_SB(0, 0), cB, voffB); PG8_STAGE(PG8_SB(0, 1), cB + hstepB, voffB); PG8_STAGE(PG8_SA(0, 0), cA, voffA); PG8_STAGE(PG8_SA(0, 1), cA + hstepA, voffA);
;     if (wr == 1) PG8_BAR;
;     PG8_WAIT_V(2); PG8_BAR;
;     PG8_STAGE(PG8_SB(1, 0), cB + kstep, voffB); PG8_STAGE(PG8_SA(1, 0), cA + kstep, voffA); PG8_STAGE(PG8_SB(1, 1), cB + hstepB + kstep, voffB);
;     PG8_WAIT_V(6); PG8_BAR;
;     for (;;) {
;         const bool has_next = S.next(ui + 1, nxt);
.LBB0_1708:
	s_lshl_b32 s6, s6, 5
	s_and_b32 s14, s6, 0x60
	s_mov_b64 s[6:7], 0x80
	s_add_i32 m0, s21, 0x18000
	v_lshl_add_u64 v[8:9], v[8:9], 0, s[6:7]
	s_lshl_b32 s9, s1, 13
	s_lshl_b32 s15, s14, 7
	s_waitcnt vmcnt(2)
	s_barrier
	global_load_lds_dwordx4 v[8:9], off
	v_lshl_add_u64 v[6:7], v[6:7], 0, s[6:7]
	s_add_i32 m0, s21, 0x1a000
	s_add_i32 s34, s21, 0x8000
	s_add_i32 s35, s21, 0xa000
	global_load_lds_dwordx4 v[6:7], off
	v_lshl_add_u64 v[2:3], v[2:3], 0, s[6:7]
	s_mov_b32 m0, s34
	s_add_u32 s10, s24, 0x40080
	global_load_lds_dwordx4 v[2:3], off
	v_lshl_add_u64 v[2:3], v[4:5], 0, s[6:7]
	s_mov_b32 m0, s35
	s_addc_u32 s11, s25, 0
	global_load_lds_dwordx4 v[2:3], off
	s_add_i32 m0, s21, 0x1c000
	v_lshl_add_u64 v[2:3], s[10:11], 0, v[132:133]
	global_load_lds_dwordx4 v[2:3], off
	v_lshl_add_u64 v[2:3], s[10:11], 0, v[136:137]
	s_add_i32 m0, s21, 0x1e000
	s_sext_i32_i8 s44, s0
	global_load_lds_dwordx4 v[2:3], off
	v_and_b32_e32 v2, 15, v0
	v_lshlrev_b32_e32 v3, 1, v13
	v_lshl_or_b32 v146, s1, 6, v2
	v_lshl_or_b32 v4, v2, 6, v3
	v_lshlrev_b32_e32 v2, 2, v2
	v_and_b32_e32 v5, 32, v2
	v_bitop3_b32 v4, v4, s9, v5 bitop3:0xde
	v_lshlrev_b32_e32 v5, 6, v0
	s_movk_i32 s0, 0x3c0
	v_and_or_b32 v3, v5, s0, v3
	s_lshl_b32 s0, s1, 8
	s_add_i32 s0, s0, 0
	v_lshlrev_b32_e32 v5, 2, v0
	s_add_i32 s0, s0, 0x20800
	v_and_b32_e32 v5, 32, v5
	v_add_u32_e32 v148, s0, v2
	v_lshlrev_b32_e32 v2, 8, v0
	v_bitop3_b32 v147, s15, v3, v5 bitop3:0xf6
	v_and_b32_e32 v2, 0x18000, v2
	v_lshlrev_b32_e32 v3, 11, v12
	v_or3_b32 v2, v10, v2, v3
	v_add_u32_e32 v138, v2, v11
	v_lshlrev_b32_e32 v2, 4, v14
	s_waitcnt vmcnt(6)
	s_cmpk_lt_u32 s8, 0x100
	v_and_b32_e32 v2, 0x38000, v2
	s_cselect_b64 s[8:9], -1, 0
	v_or3_b32 v2, v10, v2, v3
	s_add_i32 s36, 0, 0x10000
	s_add_i32 s37, 0, 0x14000
	v_or_b32_e32 v149, 16, v146
	v_or_b32_e32 v150, 32, v146
	v_or_b32_e32 v151, 48, v146
	v_or_b32_e32 v152, s14, v13
	v_mov_b32_e32 v139, v133
	v_add_u32_e32 v140, v2, v11
	v_mov_b32_e32 v141, v133
	v_mov_b64_e32 v[142:143], 0x596
	v_mov_b64_e32 v[144:145], 0x595
	v_add_u32_e32 v153, s36, v147
	v_add_u32_e32 v154, s37, v147
	v_add_u32_e32 v155, 0, v4
	s_movk_i32 s38, 0x1600
	s_mov_b32 s39, 0
	s_barrier
	s_mov_b32 s98, 0
	s_branch .LBB0_1711

; #define PG8_STAGE(bufoff, gbase, voff) do { _Pragma("unroll") for (int _i = 0; _i < 2; ++_i) \
;         __builtin_amdgcn_global_load_lds((const unsigned*)((const char*)(gbase) + (voff)[_i]), (LAS unsigned*)(lds + (bufoff) + ldsw + _i * 8192), 16, 0, 0); } while (0)
; #define PG8_LDA(dst, b, h) do { _Pragma("unroll") for (int m = 0; m < 4; ++m) _Pragma("unroll") for (int k = 0; k < 2; ++k) dst[m][k] = *(const LAS bf16x8*)(lds + PG8_SA(b, h) + aoff + m * 2048 + k * 1024); } while (0)
; #define PG8_LDB(dst, b, h) do { _Pragma("unroll") for (int n = 0; n < 2; ++n) _Pragma("unroll") for (int k = 0; k < 2; ++k) dst[n][k] = *(const LAS bf16x8*)(lds + PG8_SB(b, h) + boff + n * 2048 + k * 1024); } while (0)
; #define PG8_MMA(ai, bj, At, Bt) do { __builtin_amdgcn_s_setprio(1); _Pragma("unroll") for (int m = 0; m < 4; ++m) _Pragma("unroll") for (int n = 0; n < 2; ++n) _Pragma("unroll") for (int k = 0; k < 2; ++k) \
;         acc[ai][bj][m][n] = __builtin_amdgcn_mfma_f32_16x16x32_bf16(Bt[n][k], At[m][k], acc[ai][bj][m][n], 0, 0, 0); __builtin_amdgcn_s_setprio(0); } while (0)
; #define PG8_WAIT_V(n) asm volatile("s_waitcnt vmcnt(" #n ")" ::: "memory")
; #define PG8_WAIT_L(n) asm volatile("s_waitcnt lgkmcnt(" #n ")" ::: "memory")
; #define PG8_BAR __builtin_amdgcn_s_barrier()
; #define PG8_SCHED __builtin_amdgcn_sched_barrier(0)
; template <class Epi>
; __device__ __forceinline__ void gemm_phase(LAS unsigned char* lds, const Gemm g, const Sched& S, const Epi& E) {
;     ...
;             PG8_LDB(B0, 0, 0); PG8_LDB(B1, 0, 1); PG8_SCHED; PG8_LDA(At, 0, 0); PG8_STAGE(PG8_SA(1, 1), a1 + hstepA, voffA);
;             PG8_WAIT_V(8); PG8_WAIT_L(0); PG8_BAR; PG8_MMA(0, 0, At, B0); PG8_MMA(0, 1, At, B1); PG8_BAR; PG8_SCHED;
.LBB0_1718:
	ds_read_b128 v[156:159], v153
	ds_read_b128 v[160:163], v153 offset:1024
	ds_read_b128 v[164:167], v153 offset:2048
	ds_read_b128 v[168:171], v153 offset:3072
	ds_read_b128 v[172:175], v154
	ds_read_b128 v[176:179], v154 offset:1024
	ds_read_b128 v[180:183], v154 offset:2048
	ds_read_b128 v[184:187], v154 offset:3072
	s_add_u32 s24, s22, 0xfffc0080
	s_addc_u32 s25, s23, -1
	s_cmp_eq_u32 s53, 12
	s_cselect_b32 s27, s15, s25
	s_cselect_b32 s26, s45, s24
	s_cselect_b32 s25, s11, s52
	s_cselect_b32 s24, s46, s47
	v_lshl_add_u64 v[196:197], s[22:23], 0, v[138:139]
	s_add_i32 m0, s21, 0xc000
	ds_read_b128 v[188:191], v155
	ds_read_b128 v[192:195], v155 offset:1024
	ds_read_b128 v[200:203], v155 offset:2048
	ds_read_b128 v[204:207], v155 offset:3072
	ds_read_b128 v[208:211], v155 offset:4096
	ds_read_b128 v[212:215], v155 offset:5120
	ds_read_b128 v[216:219], v155 offset:6144
	ds_read_b128 v[220:223], v155 offset:7168
	global_load_lds_dwordx4 v[196:197], off
	v_lshl_add_u64 v[196:197], s[22:23], 0, v[140:141]
	s_add_i32 m0, s21, 0xe000
	s_nop 0
	global_load_lds_dwordx4 v[196:197], off
	s_cmp_eq_u32 s98, 0
	s_cbranch_scc1 .Lrx_p9_0_n
	s_sub_u32 s98, s98, 1
	s_waitcnt vmcnt(16)
	s_branch .Lrx_p9_0_j

; #define PG8_STAGE(bufoff, gbase, voff) do { _Pragma("unroll") for (int _i = 0; _i < 2; ++_i) \
;         __builtin_amdgcn_global_load_lds((const unsigned*)((const char*)(gbase) + (voff)[_i]), (LAS unsigned*)(lds + (bufoff) + ldsw + _i * 8192), 16, 0, 0); } while (0)
; #define PG8_LDA(dst, b, h) do { _Pragma("unroll") for (int m = 0; m < 4; ++m) _Pragma("unroll") for (int k = 0; k < 2; ++k) dst[m][k] = *(const LAS bf16x8*)(lds + PG8_SA(b, h) + aoff + m * 2048 + k * 1024); } while (0)
; #define PG8_MMA(ai, bj, At, Bt) do { __builtin_amdgcn_s_setprio(1); _Pragma("unroll") for (int m = 0; m < 4; ++m) _Pragma("unroll") for (int n = 0; n < 2; ++n) _Pragma("unroll") for (int k = 0; k < 2; ++k) \
;         acc[ai][bj][m][n] = __builtin_amdgcn_mfma_f32_16x16x32_bf16(Bt[n][k], At[m][k], acc[ai][bj][m][n], 0, 0, 0); __builtin_amdgcn_s_setprio(0); } while (0)
; #define PG8_WAIT_V(n) asm volatile("s_waitcnt vmcnt(" #n ")" ::: "memory")
; #define PG8_WAIT_L(n) asm volatile("s_waitcnt lgkmcnt(" #n ")" ::: "memory")
; #define PG8_BAR __builtin_amdgcn_s_barrier()
; #define PG8_SCHED __builtin_amdgcn_sched_barrier(0)
; template <class Epi>
; __device__ __forceinline__ void gemm_phase(LAS unsigned char* lds, const Gemm g, const Sched& S, const Epi& E) {
;     ...
;             PG8_WAIT_V(8); PG8_WAIT_L(0); PG8_BAR; PG8_MMA(0, 0, At, B0); PG8_MMA(0, 1, At, B1); PG8_BAR; PG8_SCHED;
;             PG8_LDA(At, 0, 1); PG8_STAGE(PG8_SB(0, 0), b2, voffB); PG8_STAGE(PG8_SB(0, 1), b2 + hstepB, voffB); PG8_STAGE(PG8_SA(0, 0), a2, voffA);
.Lrx_p9_0_j:
	s_waitcnt lgkmcnt(0)
	s_barrier
	s_setprio 1
	s_waitcnt lgkmcnt(0)
	v_mfma_f32_16x16x32_bf16 v[126:129], v[156:159], v[188:191], v[126:129]
	v_mfma_f32_16x16x32_bf16 v[122:125], v[164:167], v[188:191], v[122:125]
	v_mfma_f32_16x16x32_bf16 v[110:113], v[156:159], v[200:203], v[110:113]
	v_mfma_f32_16x16x32_bf16 v[106:109], v[164:167], v[200:203], v[106:109]
	v_mfma_f32_16x16x32_bf16 v[94:97], v[156:159], v[208:211], v[94:97]
	v_mfma_f32_16x16x32_bf16 v[90:93], v[164:167], v[208:211], v[90:93]
	v_mfma_f32_16x16x32_bf16 v[78:81], v[156:159], v[216:219], v[78:81]
	v_mfma_f32_16x16x32_bf16 v[74:77], v[164:167], v[216:219], v[74:77]
	v_mfma_f32_16x16x32_bf16 v[126:129], v[160:163], v[192:195], v[126:129]
	v_mfma_f32_16x16x32_bf16 v[122:125], v[168:171], v[192:195], v[122:125]
	v_mfma_f32_16x16x32_bf16 v[110:113], v[160:163], v[204:207], v[110:113]
	v_mfma_f32_16x16x32_bf16 v[106:109], v[168:171], v[204:207], v[106:109]
	v_mfma_f32_16x16x32_bf16 v[94:97], v[160:163], v[212:215], v[94:97]
	v_mfma_f32_16x16x32_bf16 v[90:93], v[168:171], v[212:215], v[90:93]
	v_mfma_f32_16x16x32_bf16 v[78:81], v[160:163], v[220:223], v[78:81]
	v_mfma_f32_16x16x32_bf16 v[74:77], v[168:171], v[220:223], v[74:77]
	s_setprio 0
	s_setprio 1
	v_mfma_f32_16x16x32_bf16 v[118:121], v[172:175], v[188:191], v[118:121]
	v_mfma_f32_16x16x32_bf16 v[114:117], v[180:183], v[188:191], v[114:117]
	v_mfma_f32_16x16x32_bf16 v[102:105], v[172:175], v[200:203], v[102:105]
	v_mfma_f32_16x16x32_bf16 v[98:101], v[180:183], v[200:203], v[98:101]
	v_mfma_f32_16x16x32_bf16 v[86:89], v[172:175], v[208:211], v[86:89]
	v_mfma_f32_16x16x32_bf16 v[82:85], v[180:183], v[208:211], v[82:85]
	v_mfma_f32_16x16x32_bf16 v[70:73], v[172:175], v[216:219], v[70:73]
	v_mfma_f32_16x16x32_bf16 v[66:69], v[180:183], v[216:219], v[66:69]
	v_mfma_f32_16x16x32_bf16 v[118:121], v[176:179], v[192:195], v[118:121]
	v_mfma_f32_16x16x32_bf16 v[114:117], v[184:187], v[192:195], v[114:117]
	v_mfma_f32_16x16x32_bf16 v[102:105], v[176:179], v[204:207], v[102:105]
	v_mfma_f32_16x16x32_bf16 v[98:101], v[184:187], v[204:207], v[98:101]
	v_mfma_f32_16x16x32_bf16 v[86:89], v[176:179], v[212:215], v[86:89]
	v_mfma_f32_16x16x32_bf16 v[82:85], v[184:187], v[212:215], v[82:85]
	v_mfma_f32_16x16x32_bf16 v[70:73], v[176:179], v[220:223], v[70:73]
	v_mfma_f32_16x16x32_bf16 v[66:69], v[184:187], v[220:223], v[66:69]
	s_setprio 0
	s_barrier
	s_add_i32 s54, s36, s29
	v_lshl_add_u64 v[196:197], s[24:25], 0, v[132:133]
	s_mov_b32 m0, s54
	ds_read_b128 v[188:191], v155 offset:16384
	ds_read_b128 v[192:195], v155 offset:17408
	ds_read_b128 v[200:203], v155 offset:18432
	ds_read_b128 v[204:207], v155 offset:19456
	ds_read_b128 v[208:211], v155 offset:20480
	ds_read_b128 v[212:215], v155 offset:21504
	ds_read_b128 v[216:219], v155 offset:22528
	ds_read_b128 v[220:223], v155 offset:23552
	global_load_lds_dwordx4 v[196:197], off
	s_add_i32 m0, s54, 0x2000
	s_add_u32 s54, s24, 0x40000
	v_lshl_add_u64 v[224:225], s[24:25], 0, v[136:137]
	s_addc_u32 s55, s25, 0
	s_add_i32 s56, s37, s29
	global_load_lds_dwordx4 v[224:225], off
	v_lshl_add_u64 v[226:227], s[54:55], 0, v[132:133]
	s_mov_b32 m0, s56
	v_lshl_add_u64 v[228:229], s[26:27], 0, v[134:135]
	global_load_lds_dwordx4 v[226:227], off
	v_lshl_add_u64 v[226:227], s[54:55], 0, v[136:137]
	s_add_i32 m0, s56, 0x2000
	s_nop 0
	global_load_lds_dwordx4 v[226:227], off
	v_lshl_add_u64 v[226:227], s[26:27], 0, v[130:131]
	s_mov_b32 m0, s21
	s_nop 0
	global_load_lds_dwordx4 v[226:227], off
	s_mov_b32 m0, s30
	s_nop 0
	global_load_lds_dwordx4 v[228:229], off
	s_cmp_eq_u32 s98, 0
	s_cbranch_scc1 .Lrx_p9_1_n
	s_sub_u32 s98, s98, 1
	s_waitcnt vmcnt(16)
	s_branch .Lrx_p9_1_j

; #define PG8_STAGE(bufoff, gbase, voff) do { _Pragma("unroll") for (int _i = 0; _i < 2; ++_i) \
;         __builtin_amdgcn_global_load_lds((const unsigned*)((const char*)(gbase) + (voff)[_i]), (LAS unsigned*)(lds + (bufoff) + ldsw + _i * 8192), 16, 0, 0); } while (0)
; #define PG8_LDA(dst, b, h) do { _Pragma("unroll") for (int m = 0; m < 4; ++m) _Pragma("unroll") for (int k = 0; k < 2; ++k) dst[m][k] = *(const LAS bf16x8*)(lds + PG8_SA(b, h) + aoff + m * 2048 + k * 1024); } while (0)
; #define PG8_LDB(dst, b, h) do { _Pragma("unroll") for (int n = 0; n < 2; ++n) _Pragma("unroll") for (int k = 0; k < 2; ++k) dst[n][k] = *(const LAS bf16x8*)(lds + PG8_SB(b, h) + boff + n * 2048 + k * 1024); } while (0)
; #define PG8_MMA(ai, bj, At, Bt) do { __builtin_amdgcn_s_setprio(1); _Pragma("unroll") for (int m = 0; m < 4; ++m) _Pragma("unroll") for (int n = 0; n < 2; ++n) _Pragma("unroll") for (int k = 0; k < 2; ++k) \
;         acc[ai][bj][m][n] = __builtin_amdgcn_mfma_f32_16x16x32_bf16(Bt[n][k], At[m][k], acc[ai][bj][m][n], 0, 0, 0); __builtin_amdgcn_s_setprio(0); } while (0)
; #define PG8_WAIT_V(n) asm volatile("s_waitcnt vmcnt(" #n ")" ::: "memory")
; #define PG8_WAIT_L(n) asm volatile("s_waitcnt lgkmcnt(" #n ")" ::: "memory")
; #define PG8_BAR __builtin_amdgcn_s_barrier()
; #define PG8_SCHED __builtin_amdgcn_sched_barrier(0)
; template <class Epi>
; __device__ __forceinline__ void gemm_phase(LAS unsigned char* lds, const Gemm g, const Sched& S, const Epi& E) {
;     ...
;             PG8_WAIT_V(8); PG8_WAIT_L(0); PG8_BAR; PG8_MMA(1, 0, At, B0); PG8_MMA(1, 1, At, B1); PG8_BAR; PG8_SCHED;
;             PG8_LDB(B0, 1, 0); PG8_LDB(B1, 1, 1); PG8_SCHED; PG8_LDA(At, 1, 0); PG8_STAGE(PG8_SA(0, 1), a2 + hstepA, voffA);
;             PG8_WAIT_V(8); PG8_WAIT_L(0); PG8_BAR; PG8_MMA(0, 0, At, B0); PG8_MMA(0, 1, At, B1); PG8_BAR; PG8_SCHED;
.Lrx_p9_1_j:
	s_waitcnt lgkmcnt(0)
	s_barrier
	s_setprio 1
	s_waitcnt lgkmcnt(0)
	v_mfma_f32_16x16x32_bf16 v[62:65], v[156:159], v[188:191], v[62:65]
	v_mfma_f32_16x16x32_bf16 v[58:61], v[164:167], v[188:191], v[58:61]
	v_mfma_f32_16x16x32_bf16 v[46:49], v[156:159], v[200:203], v[46:49]
	v_mfma_f32_16x16x32_bf16 v[42:45], v[164:167], v[200:203], v[42:45]
	v_mfma_f32_16x16x32_bf16 v[30:33], v[156:159], v[208:211], v[30:33]
	v_mfma_f32_16x16x32_bf16 v[26:29], v[164:167], v[208:211], v[26:29]
	v_mfma_f32_16x16x32_bf16 v[14:17], v[156:159], v[216:219], v[14:17]
	v_mfma_f32_16x16x32_bf16 v[10:13], v[164:167], v[216:219], v[10:13]
	v_mfma_f32_16x16x32_bf16 v[62:65], v[160:163], v[192:195], v[62:65]
	v_mfma_f32_16x16x32_bf16 v[58:61], v[168:171], v[192:195], v[58:61]
	v_mfma_f32_16x16x32_bf16 v[46:49], v[160:163], v[204:207], v[46:49]
	v_mfma_f32_16x16x32_bf16 v[42:45], v[168:171], v[204:207], v[42:45]
	v_mfma_f32_16x16x32_bf16 v[30:33], v[160:163], v[212:215], v[30:33]
	v_mfma_f32_16x16x32_bf16 v[26:29], v[168:171], v[212:215], v[26:29]
	v_mfma_f32_16x16x32_bf16 v[14:17], v[160:163], v[220:223], v[14:17]
	v_mfma_f32_16x16x32_bf16 v[10:13], v[168:171], v[220:223], v[10:13]
	s_setprio 0
	s_setprio 1
	v_mfma_f32_16x16x32_bf16 v[54:57], v[172:175], v[188:191], v[54:57]
	v_mfma_f32_16x16x32_bf16 v[50:53], v[180:183], v[188:191], v[50:53]
	v_mfma_f32_16x16x32_bf16 v[38:41], v[172:175], v[200:203], v[38:41]
	v_mfma_f32_16x16x32_bf16 v[34:37], v[180:183], v[200:203], v[34:37]
	v_mfma_f32_16x16x32_bf16 v[22:25], v[172:175], v[208:211], v[22:25]
	v_mfma_f32_16x16x32_bf16 v[18:21], v[180:183], v[208:211], v[18:21]
	v_mfma_f32_16x16x32_bf16 v[6:9], v[172:175], v[216:219], v[6:9]
	v_mfma_f32_16x16x32_bf16 v[2:5], v[180:183], v[216:219], v[2:5]
	v_mfma_f32_16x16x32_bf16 v[54:57], v[176:179], v[192:195], v[54:57]
	v_mfma_f32_16x16x32_bf16 v[50:53], v[184:187], v[192:195], v[50:53]
	v_mfma_f32_16x16x32_bf16 v[38:41], v[176:179], v[204:207], v[38:41]
	v_mfma_f32_16x16x32_bf16 v[34:37], v[184:187], v[204:207], v[34:37]
	v_mfma_f32_16x16x32_bf16 v[22:25], v[176:179], v[212:215], v[22:25]
	v_mfma_f32_16x16x32_bf16 v[18:21], v[184:187], v[212:215], v[18:21]
	v_mfma_f32_16x16x32_bf16 v[6:9], v[176:179], v[220:223], v[6:9]
	v_mfma_f32_16x16x32_bf16 v[2:5], v[184:187], v[220:223], v[2:5]
	s_setprio 0
	s_barrier
	s_add_i32 s54, 0, 0x18000
	s_add_i32 s55, 0, 0x1c000
	v_add_u32_e32 v168, s54, v147
	v_add_u32_e32 v184, s55, v147
	ds_read_b128 v[156:159], v168
	ds_read_b128 v[160:163], v168 offset:1024
	ds_read_b128 v[164:167], v168 offset:2048
	ds_read_b128 v[168:171], v168 offset:3072
	ds_read_b128 v[172:175], v184
	ds_read_b128 v[176:179], v184 offset:1024
	ds_read_b128 v[180:183], v184 offset:2048
	ds_read_b128 v[184:187], v184 offset:3072
	s_add_u32 s26, s26, 0x40000
	s_addc_u32 s27, s27, 0
	s_mov_b32 m0, s31
	v_lshl_add_u64 v[230:231], s[26:27], 0, v[130:131]
	ds_read_b128 v[188:191], v155 offset:32768
	ds_read_b128 v[192:195], v155 offset:33792
	ds_read_b128 v[200:203], v155 offset:34816
	ds_read_b128 v[204:207], v155 offset:35840
	ds_read_b128 v[208:211], v155 offset:36864
	ds_read_b128 v[212:215], v155 offset:37888
	ds_read_b128 v[216:219], v155 offset:38912
	ds_read_b128 v[220:223], v155 offset:39936
	global_load_lds_dwordx4 v[230:231], off
	v_lshl_add_u64 v[230:231], s[26:27], 0, v[134:135]
	s_mov_b32 m0, s33
	s_nop 0
	global_load_lds_dwordx4 v[230:231], off
	s_waitcnt vmcnt(8)
	s_waitcnt lgkmcnt(0)
	s_barrier
	s_setprio 1
	s_waitcnt lgkmcnt(0)
	v_mfma_f32_16x16x32_bf16 v[126:129], v[156:159], v[188:191], v[126:129]
	v_mfma_f32_16x16x32_bf16 v[122:125], v[164:167], v[188:191], v[122:125]
	v_mfma_f32_16x16x32_bf16 v[110:113], v[156:159], v[200:203], v[110:113]
	v_mfma_f32_16x16x32_bf16 v[106:109], v[164:167], v[200:203], v[106:109]
	v_mfma_f32_16x16x32_bf16 v[94:97], v[156:159], v[208:211], v[94:97]
	v_mfma_f32_16x16x32_bf16 v[90:93], v[164:167], v[208:211], v[90:93]
	v_mfma_f32_16x16x32_bf16 v[78:81], v[156:159], v[216:219], v[78:81]
	v_mfma_f32_16x16x32_bf16 v[74:77], v[164:167], v[216:219], v[74:77]
	v_mfma_f32_16x16x32_bf16 v[126:129], v[160:163], v[192:195], v[126:129]
	v_mfma_f32_16x16x32_bf16 v[122:125], v[168:171], v[192:195], v[122:125]
	v_mfma_f32_16x16x32_bf16 v[110:113], v[160:163], v[204:207], v[110:113]
	v_mfma_f32_16x16x32_bf16 v[106:109], v[168:171], v[204:207], v[106:109]
	v_mfma_f32_16x16x32_bf16 v[94:97], v[160:163], v[212:215], v[94:97]
	v_mfma_f32_16x16x32_bf16 v[90:93], v[168:171], v[212:215], v[90:93]
	v_mfma_f32_16x16x32_bf16 v[78:81], v[160:163], v[220:223], v[78:81]
	v_mfma_f32_16x16x32_bf16 v[74:77], v[168:171], v[220:223], v[74:77]
	s_setprio 0
	s_setprio 1
	v_mfma_f32_16x16x32_bf16 v[118:121], v[172:175], v[188:191], v[118:121]
	v_mfma_f32_16x16x32_bf16 v[114:117], v[180:183], v[188:191], v[114:117]
	v_mfma_f32_16x16x32_bf16 v[102:105], v[172:175], v[200:203], v[102:105]
	v_mfma_f32_16x16x32_bf16 v[98:101], v[180:183], v[200:203], v[98:101]
	v_mfma_f32_16x16x32_bf16 v[86:89], v[172:175], v[208:211], v[86:89]
	v_mfma_f32_16x16x32_bf16 v[82:85], v[180:183], v[208:211], v[82:85]
	v_mfma_f32_16x16x32_bf16 v[70:73], v[172:175], v[216:219], v[70:73]
	v_mfma_f32_16x16x32_bf16 v[66:69], v[180:183], v[216:219], v[66:69]
	v_mfma_f32_16x16x32_bf16 v[118:121], v[176:179], v[192:195], v[118:121]
	v_mfma_f32_16x16x32_bf16 v[114:117], v[184:187], v[192:195], v[114:117]
	v_mfma_f32_16x16x32_bf16 v[102:105], v[176:179], v[204:207], v[102:105]
	v_mfma_f32_16x16x32_bf16 v[98:101], v[184:187], v[204:207], v[98:101]
	v_mfma_f32_16x16x32_bf16 v[86:89], v[176:179], v[212:215], v[86:89]
	v_mfma_f32_16x16x32_bf16 v[82:85], v[184:187], v[212:215], v[82:85]
	v_mfma_f32_16x16x32_bf16 v[70:73], v[176:179], v[220:223], v[70:73]
	v_mfma_f32_16x16x32_bf16 v[66:69], v[184:187], v[220:223], v[66:69]
	s_setprio 0
	s_barrier
; #define PG8_STAGE(bufoff, gbase, voff) do { _Pragma("unroll") for (int _i = 0; _i < 2; ++_i) \
;         __builtin_amdgcn_global_load_lds((const unsigned*)((const char*)(gbase) + (voff)[_i]), (LAS unsigned*)(lds + (bufoff) + ldsw + _i * 8192), 16, 0, 0); } while (0)
; #define PG8_LDA(dst, b, h) do { _Pragma("unroll") for (int m = 0; m < 4; ++m) _Pragma("unroll") for (int k = 0; k < 2; ++k) dst[m][k] = *(const LAS bf16x8*)(lds + PG8_SA(b, h) + aoff + m * 2048 + k * 1024); } while (0)
; #define PG8_MMA(ai, bj, At, Bt) do { __builtin_amdgcn_s_setprio(1); _Pragma("unroll") for (int m = 0; m < 4; ++m) _Pragma("unroll") for (int n = 0; n < 2; ++n) _Pragma("unroll") for (int k = 0; k < 2; ++k) \
;         acc[ai][bj][m][n] = __builtin_amdgcn_mfma_f32_16x16x32_bf16(Bt[n][k], At[m][k], acc[ai][bj][m][n], 0, 0, 0); __builtin_amdgcn_s_setprio(0); } while (0)
; #define PG8_WAIT_V(n) asm volatile("s_waitcnt vmcnt(" #n ")" ::: "memory")
; #define PG8_WAIT_L(n) asm volatile("s_waitcnt lgkmcnt(" #n ")" ::: "memory")
; #define PG8_BAR __builtin_amdgcn_s_barrier()
; #define PG8_SCHED __builtin_amdgcn_sched_barrier(0)
; template <class Epi>
; __device__ __forceinline__ void gemm_phase(LAS unsigned char* lds, const Gemm g, const Sched& S, const Epi& E) {
;     ...
;             PG8_WAIT_V(8); PG8_WAIT_L(0); PG8_BAR; PG8_MMA(0, 0, At, B0); PG8_MMA(0, 1, At, B1); PG8_BAR; PG8_SCHED;
;             PG8_LDA(At, 1, 1); PG8_STAGE(PG8_SB(1, 0), b3, voffB); PG8_STAGE(PG8_SB(1, 1), b3 + hstepB, voffB); PG8_STAGE(PG8_SA(1, 0), a3, voffA);
;             PG8_WAIT_V(8); PG8_WAIT_L(0); PG8_BAR; PG8_MMA(1, 0, At, B0); PG8_MMA(1, 1, At, B1); PG8_BAR; PG8_SCHED;
;         }
;         if (wr == 0) PG8_BAR;
	s_add_i32 s26, s54, s29
	v_lshl_add_u64 v[196:197], v[196:197], 0, s[6:7]
	s_mov_b32 m0, s26
	ds_read_b128 v[188:191], v155 offset:49152
	ds_read_b128 v[192:195], v155 offset:50176
	ds_read_b128 v[200:203], v155 offset:51200
	ds_read_b128 v[204:207], v155 offset:52224
	ds_read_b128 v[208:211], v155 offset:53248
	ds_read_b128 v[212:215], v155 offset:54272
	ds_read_b128 v[216:219], v155 offset:55296
	ds_read_b128 v[220:223], v155 offset:56320
	global_load_lds_dwordx4 v[196:197], off
	s_add_i32 m0, s26, 0x2000
	s_add_u32 s24, s24, 0x40080
	v_lshl_add_u64 v[196:197], v[224:225], 0, s[6:7]
	s_addc_u32 s25, s25, 0
	s_add_i32 s26, s55, s29
	global_load_lds_dwordx4 v[196:197], off
	v_lshl_add_u64 v[196:197], s[24:25], 0, v[132:133]
	s_mov_b32 m0, s26
	s_nop 0
	global_load_lds_dwordx4 v[196:197], off
	v_lshl_add_u64 v[196:197], s[24:25], 0, v[136:137]
	s_add_i32 m0, s26, 0x2000
	s_nop 0
	global_load_lds_dwordx4 v[196:197], off
	v_lshl_add_u64 v[196:197], v[226:227], 0, s[6:7]
	s_mov_b32 m0, s34
	s_nop 0
	global_load_lds_dwordx4 v[196:197], off
	v_lshl_add_u64 v[196:197], v[228:229], 0, s[6:7]
	s_mov_b32 m0, s35
	s_nop 0
	global_load_lds_dwordx4 v[196:197], off
	s_waitcnt vmcnt(8)
	s_waitcnt lgkmcnt(0)
	s_barrier
	s_setprio 1
	s_waitcnt lgkmcnt(0)
	v_mfma_f32_16x16x32_bf16 v[62:65], v[156:159], v[188:191], v[62:65]
	v_mfma_f32_16x16x32_bf16 v[58:61], v[164:167], v[188:191], v[58:61]
	v_mfma_f32_16x16x32_bf16 v[46:49], v[156:159], v[200:203], v[46:49]
	v_mfma_f32_16x16x32_bf16 v[42:45], v[164:167], v[200:203], v[42:45]
	v_mfma_f32_16x16x32_bf16 v[30:33], v[156:159], v[208:211], v[30:33]
	v_mfma_f32_16x16x32_bf16 v[26:29], v[164:167], v[208:211], v[26:29]
	v_mfma_f32_16x16x32_bf16 v[14:17], v[156:159], v[216:219], v[14:17]
	v_mfma_f32_16x16x32_bf16 v[10:13], v[164:167], v[216:219], v[10:13]
	v_mfma_f32_16x16x32_bf16 v[62:65], v[160:163], v[192:195], v[62:65]
	v_mfma_f32_16x16x32_bf16 v[58:61], v[168:171], v[192:195], v[58:61]
	v_mfma_f32_16x16x32_bf16 v[46:49], v[160:163], v[204:207], v[46:49]
	v_mfma_f32_16x16x32_bf16 v[42:45], v[168:171], v[204:207], v[42:45]
	v_mfma_f32_16x16x32_bf16 v[30:33], v[160:163], v[212:215], v[30:33]
	v_mfma_f32_16x16x32_bf16 v[26:29], v[168:171], v[212:215], v[26:29]
	v_mfma_f32_16x16x32_bf16 v[14:17], v[160:163], v[220:223], v[14:17]
	v_mfma_f32_16x16x32_bf16 v[10:13], v[168:171], v[220:223], v[10:13]
	s_setprio 0
	s_setprio 1
	v_mfma_f32_16x16x32_bf16 v[54:57], v[172:175], v[188:191], v[54:57]
	v_mfma_f32_16x16x32_bf16 v[50:53], v[180:183], v[188:191], v[50:53]
	v_mfma_f32_16x16x32_bf16 v[38:41], v[172:175], v[200:203], v[38:41]
	v_mfma_f32_16x16x32_bf16 v[34:37], v[180:183], v[200:203], v[34:37]
	v_mfma_f32_16x16x32_bf16 v[22:25], v[172:175], v[208:211], v[22:25]
	v_mfma_f32_16x16x32_bf16 v[18:21], v[180:183], v[208:211], v[18:21]
	v_mfma_f32_16x16x32_bf16 v[6:9], v[172:175], v[216:219], v[6:9]
	v_mfma_f32_16x16x32_bf16 v[2:5], v[180:183], v[216:219], v[2:5]
	v_mfma_f32_16x16x32_bf16 v[54:57], v[176:179], v[192:195], v[54:57]
	v_mfma_f32_16x16x32_bf16 v[50:53], v[184:187], v[192:195], v[50:53]
	v_mfma_f32_16x16x32_bf16 v[38:41], v[176:179], v[204:207], v[38:41]
	v_mfma_f32_16x16x32_bf16 v[34:37], v[184:187], v[204:207], v[34:37]
	v_mfma_f32_16x16x32_bf16 v[22:25], v[176:179], v[212:215], v[22:25]
	v_mfma_f32_16x16x32_bf16 v[18:21], v[184:187], v[212:215], v[18:21]
	v_mfma_f32_16x16x32_bf16 v[6:9], v[176:179], v[220:223], v[6:9]
	v_mfma_f32_16x16x32_bf16 v[2:5], v[184:187], v[220:223], v[2:5]
	s_setprio 0
	s_barrier
	s_add_i32 s53, s53, 2
	s_add_u32 s22, s22, 0x100
	s_addc_u32 s23, s23, 0
	s_add_u32 s47, s47, 0x100
	s_addc_u32 s52, s52, 0
	s_cmp_gt_u32 s53, 13
	s_cbranch_scc0 .LBB0_1718
	s_and_b64 vcc, exec, s[8:9]
	s_cbranch_vccz .LBB0_1721
	s_barrier
